# mixed phase: next queue item fetched (atomic) at the start of the current item and consumed at its end
# speedup vs baseline: 1.0033x; 1.0033x over previous
.LBB0_84:
	s_mov_b32 s100, 0
	s_and_b32 s0, s58, 7
	s_lshl_b32 s2, s0, 8
	s_lshl_b32 s12, s0, 6
	s_add_i32 s0, s57, s99
	s_and_b32 s10, s0, 7
	s_lshl_b32 s0, s10, 4
	v_readlane_b32 s1, v246, 28
	s_or_b32 s0, s0, s1
	s_ashr_i32 s1, s0, 31
	s_lshl_b64 s[0:1], s[0:1], 2
	s_add_u32 s48, s78, s0
	s_mul_i32 s0, s10, 0xa0
	s_addc_u32 s49, s79, s1
	s_addk_i32 s0, 0xfe98
	v_writelane_b32 v246, s0, 63
	s_lshl_b32 s0, s10, 6
	s_addk_i32 s0, 0x6d8
	s_lshl_b32 s11, s10, 5
	v_writelane_b32 v245, s0, 0
	s_lshl_b32 s0, s10, 8
	s_sub_i32 s0, s0, 40
	v_writelane_b32 v245, s0, 1
	s_lshl_b32 s10, s10, 3
	s_add_i32 s11, s11, -8
	s_add_i32 s0, s12, 0x6d8
	s_sub_i32 s45, s2, 40
	v_writelane_b32 v245, s0, 2
	s_branch .LBB0_87
.Lmix_pf_top:
	v_mov_b32_e32 v1, s8
	s_waitcnt lgkmcnt(0)
	s_barrier
	s_branch .Lmix_pf_join

.LBB0_87:
	s_cmp_eq_u32 s100, 1
	s_cbranch_scc1 .Lmix_pf_top
	s_waitcnt vmcnt(0) lgkmcnt(0)
	s_barrier
	s_and_saveexec_b64 s[0:1], s[46:47]
	s_cbranch_execz .LBB0_91
	s_mov_b64 s[40:41], exec
	v_mbcnt_lo_u32_b32 v1, s40, 0
	v_mbcnt_hi_u32_b32 v1, s41, v1
	v_cmp_eq_u32_e32 vcc, 0, v1
	s_and_saveexec_b64 s[12:13], vcc
	s_cbranch_execz .LBB0_90
	s_bcnt1_i32_b64 s2, s[40:41]
	v_mov_b32_e32 v2, s2
	global_atomic_add v2, v0, v2, s[48:49] sc0

.Lmix_pf_join:
	ds_read_b32 v1, v1
	s_mov_b64 s[0:1], -1
	s_waitcnt lgkmcnt(0)
	v_readfirstlane_b32 s97, v1
	s_cmpk_gt_i32 s97, 0x207
	s_cbranch_scc1 .LBB0_86
	s_mov_b32 s100, 0
	s_cmp_lt_u32 s97, 40
	s_cbranch_scc1 .Lmix_nopf
	s_cmpk_gt_u32 s97, 0x1c7
	s_cbranch_scc1 .Lmix_nopf
	s_mov_b32 s100, 1
	s_and_saveexec_b64 s[42:43], s[46:47]
	s_cbranch_execz .Lmix_pf_issued
	v_mov_b32_e32 v250, 1
	global_atomic_add v249, v0, v250, s[48:49] sc0

.Lmix_nopf:
	s_cmp_gt_i32 s97, 7
	s_cbranch_scc0 .LBB0_150
	s_cmp_gt_u32 s97, 39
	s_cbranch_scc0 .LBB0_145
	s_cmpk_gt_u32 s97, 0x127
	s_cbranch_scc0 .LBB0_109
	s_cmpk_gt_u32 s97, 0x167
	s_cbranch_scc0 .LBB0_97
	v_readlane_b32 s0, v246, 63
	s_add_i32 s0, s0, s97
	v_mov_b32_e32 v47, v149
	s_lshl_b32 s0, s0, 5
	s_and_b32 s12, s0, 0xff80
	v_ashrrev_i32_e32 v2, 1, v47
	s_and_b32 s13, s97, 3
	v_add_u32_e32 v2, s12, v2
	v_mov_b64_e32 v[34:35], s[34:35]
	v_lshlrev_b32_e32 v4, 5, v47
	v_mad_i64_i32 v[2:3], s[0:1], v2, s9, v[34:35]
	s_lshl_b32 s2, s13, 7
	v_and_b32_e32 v17, 32, v4
	v_lshl_add_u64 v[2:3], v[2:3], 0, s[2:3]
	v_lshlrev_b32_e32 v4, 1, v17
	v_mov_b32_e32 v5, v0
	v_lshl_add_u64 v[8:9], v[2:3], 0, v[4:5]
	global_load_dwordx4 v[4:7], v[8:9], off offset:3072
	global_load_dwordx4 v[28:31], v[8:9], off offset:3120
	global_load_dwordx4 v[252:255], v[8:9], off offset:3088
	global_load_dwordx4 v[92:95], v[8:9], off offset:3104
	s_lshl_b32 s0, s13, 8
	v_readlane_b32 s1, v246, 30
	s_add_u32 s40, s1, s0
	v_readlane_b32 s1, v246, 31
	s_addc_u32 s41, s1, 0
	v_readlane_b32 s1, v246, 32
	s_add_u32 s0, s1, s0
	v_readlane_b32 s1, v246, 33
	s_addc_u32 s1, s1, 0
	v_readlane_b32 s42, v248, 7
	v_readlane_b32 s43, v248, 8
	v_and_b32_e32 v46, 15, v47
	v_ashrrev_i32_e32 v1, 6, v47
	v_readlane_b32 s60, v246, 5
	v_readlane_b32 s74, v246, 19
	v_readlane_b32 s75, v246, 20
	v_readlane_b32 s64, v246, 9
	v_readlane_b32 s65, v246, 10
	v_readlane_b32 s66, v246, 11
	v_readlane_b32 s67, v246, 12
	v_readlane_b32 s68, v246, 13
	v_readlane_b32 s69, v246, 14
	v_readlane_b32 s70, v246, 15
	v_readlane_b32 s71, v246, 16
	v_readlane_b32 s72, v246, 17
	v_readlane_b32 s73, v246, 18
	v_readlane_b32 s61, v246, 6
	v_readlane_b32 s62, v246, 7
	v_readlane_b32 s63, v246, 8
	s_waitcnt vmcnt(3)
	v_lshlrev_b32_e32 v2, 16, v4
	v_and_b32_e32 v20, 0xffff0000, v4
	v_lshlrev_b32_e32 v18, 16, v5
	v_and_b32_e32 v15, 0xffff0000, v5
	v_lshlrev_b32_e32 v13, 16, v6
	v_and_b32_e32 v12, 0xffff0000, v6
	v_lshlrev_b32_e32 v11, 16, v7
	v_and_b32_e32 v10, 0xffff0000, v7
	s_waitcnt vmcnt(1)
	v_mov_b32_e32 v4, v252
	v_mov_b32_e32 v5, v253
	v_mov_b32_e32 v6, v254
	v_mov_b32_e32 v7, v255
	v_add_f32_e32 v3, 0, v2
	v_add_f32_e32 v3, v3, v20
	v_add_f32_e32 v3, v3, v18
	v_add_f32_e32 v3, v3, v15
	v_add_f32_e32 v3, v3, v13
	v_add_f32_e32 v3, v3, v12
	v_add_f32_e32 v3, v3, v11
	v_add_f32_e32 v3, v3, v10
	s_waitcnt vmcnt(0)
	v_lshlrev_b32_e32 v25, 16, v4
	v_and_b32_e32 v24, 0xffff0000, v4
	v_lshlrev_b32_e32 v23, 16, v5
	v_and_b32_e32 v22, 0xffff0000, v5
	v_lshlrev_b32_e32 v21, 16, v6
	v_and_b32_e32 v19, 0xffff0000, v6
	v_lshlrev_b32_e32 v16, 16, v7
	v_and_b32_e32 v14, 0xffff0000, v7
	v_mov_b32_e32 v4, v92
	v_mov_b32_e32 v5, v93
	v_mov_b32_e32 v6, v94
	v_mov_b32_e32 v7, v95
	v_add_f32_e32 v3, v3, v25
	v_add_f32_e32 v3, v3, v24
	v_add_f32_e32 v3, v3, v23
	v_add_f32_e32 v3, v3, v22
	v_add_f32_e32 v3, v3, v21
	v_add_f32_e32 v3, v3, v19
	v_add_f32_e32 v3, v3, v16
	v_add_f32_e32 v3, v3, v14
	v_and_b32_e32 v9, 0xffff0000, v30
	v_lshlrev_b32_e32 v8, 16, v30
	v_lshlrev_b32_e32 v30, 16, v29
	s_waitcnt vmcnt(0)
	v_lshlrev_b32_e32 v26, 16, v4
	v_and_b32_e32 v52, 0xffff0000, v4
	v_add_f32_e32 v3, v3, v26
	v_lshlrev_b32_e32 v51, 16, v5
	v_add_f32_e32 v3, v3, v52
	v_and_b32_e32 v50, 0xffff0000, v5
	v_add_f32_e32 v3, v3, v51
	v_lshlrev_b32_e32 v49, 16, v6
	v_add_f32_e32 v3, v3, v50
	v_and_b32_e32 v5, 64, v223
	v_and_b32_e32 v48, 0xffff0000, v6
	v_add_f32_e32 v3, v3, v49
	v_xor_b32_e32 v4, 1, v223
	v_add_u32_e32 v5, 64, v5
	v_add_f32_e32 v3, v3, v48
	v_cmp_lt_i32_e32 vcc, v4, v5
	v_lshlrev_b32_e32 v32, 16, v7
	v_and_b32_e32 v33, 0xffff0000, v7
	v_cndmask_b32_e32 v4, v223, v4, vcc
	v_add_f32_e32 v3, v3, v32
	v_lshlrev_b32_e32 v27, 2, v4
	v_and_b32_e32 v5, 0xffff0000, v31
	v_lshlrev_b32_e32 v4, 16, v31
	v_and_b32_e32 v31, 0xffff0000, v29
	v_and_b32_e32 v29, 0xffff0000, v28
	v_lshlrev_b32_e32 v28, 16, v28
	v_add_f32_e32 v3, v3, v33
	v_add_f32_e32 v3, v3, v28
	v_add_f32_e32 v3, v3, v29
	v_add_f32_e32 v3, v3, v30
	v_add_f32_e32 v3, v3, v31
	v_add_f32_e32 v3, v3, v8
	v_add_f32_e32 v3, v3, v9
	v_add_f32_e32 v3, v3, v4
	v_add_f32_e32 v3, v3, v5
	ds_bpermute_b32 v6, v27, v3
	s_waitcnt lgkmcnt(0)
	v_add_f32_e32 v3, v3, v6
	v_fmac_f32_e32 v20, 0xbc800000, v3
	v_fmac_f32_e32 v2, 0xbc800000, v3
	v_mul_f32_e32 v7, v20, v20
	v_fmac_f32_e32 v7, v2, v2
	v_fmac_f32_e32 v18, 0xbc800000, v3
	v_fmac_f32_e32 v7, v18, v18
	v_fmac_f32_e32 v15, 0xbc800000, v3
	v_fmac_f32_e32 v7, v15, v15
	v_fmac_f32_e32 v13, 0xbc800000, v3
	v_fmac_f32_e32 v7, v13, v13
	v_fmac_f32_e32 v12, 0xbc800000, v3
	v_fmac_f32_e32 v7, v12, v12
	v_fmac_f32_e32 v11, 0xbc800000, v3
	v_fmac_f32_e32 v7, v11, v11
	v_fmac_f32_e32 v10, 0xbc800000, v3
	v_fmac_f32_e32 v7, v10, v10
	v_fmac_f32_e32 v25, 0xbc800000, v3
	v_fmac_f32_e32 v7, v25, v25
	v_fmac_f32_e32 v24, 0xbc800000, v3
	v_fmac_f32_e32 v7, v24, v24
	v_fmac_f32_e32 v23, 0xbc800000, v3
	v_fmac_f32_e32 v7, v23, v23
	v_fmac_f32_e32 v22, 0xbc800000, v3
	v_fmac_f32_e32 v7, v22, v22
	v_fmac_f32_e32 v21, 0xbc800000, v3
	v_fmac_f32_e32 v7, v21, v21
	v_fmac_f32_e32 v19, 0xbc800000, v3
	v_fmac_f32_e32 v7, v19, v19
	v_fmac_f32_e32 v16, 0xbc800000, v3
	v_fmac_f32_e32 v7, v16, v16
	v_fmac_f32_e32 v14, 0xbc800000, v3
	v_fmac_f32_e32 v7, v14, v14
	v_fmac_f32_e32 v26, 0xbc800000, v3
	v_fmac_f32_e32 v7, v26, v26
	v_fmac_f32_e32 v52, 0xbc800000, v3
	v_fmac_f32_e32 v7, v52, v52
	v_fmac_f32_e32 v51, 0xbc800000, v3
	v_fmac_f32_e32 v7, v51, v51
	v_fmac_f32_e32 v50, 0xbc800000, v3
	v_fmac_f32_e32 v7, v50, v50
	v_fmac_f32_e32 v49, 0xbc800000, v3
	v_fmac_f32_e32 v7, v49, v49
	v_fmac_f32_e32 v48, 0xbc800000, v3
	v_mul_f32_e32 v6, 0x3c800000, v3
	v_fmac_f32_e32 v7, v48, v48
	v_pk_add_f32 v[44:45], v[32:33], v[6:7] op_sel_hi:[1,0] neg_lo:[0,1] neg_hi:[0,1]
	v_pk_add_f32 v[42:43], v[28:29], v[6:7] op_sel_hi:[1,0] neg_lo:[0,1] neg_hi:[0,1]
	v_pk_mul_f32 v[32:33], v[44:45], v[44:45]
	v_pk_mul_f32 v[28:29], v[42:43], v[42:43]
	v_add_f32_e32 v3, v32, v7
	v_add_f32_e32 v3, v33, v3
	v_add_f32_e32 v3, v28, v3
	v_pk_add_f32 v[40:41], v[30:31], v[6:7] op_sel_hi:[1,0] neg_lo:[0,1] neg_hi:[0,1]
	v_add_f32_e32 v3, v29, v3
	v_pk_mul_f32 v[28:29], v[40:41], v[40:41]
	v_pk_add_f32 v[38:39], v[8:9], v[6:7] op_sel_hi:[1,0] neg_lo:[0,1] neg_hi:[0,1]
	v_add_f32_e32 v3, v28, v3
	v_add_f32_e32 v3, v29, v3
	v_pk_mul_f32 v[8:9], v[38:39], v[38:39]
	v_pk_add_f32 v[36:37], v[4:5], v[6:7] op_sel_hi:[1,0] neg_lo:[0,1] neg_hi:[0,1]
	v_add_f32_e32 v3, v8, v3
	v_add_f32_e32 v3, v9, v3
	v_pk_mul_f32 v[4:5], v[36:37], v[36:37]
	v_lshlrev_b32_e32 v30, 2, v17
	v_add_f32_e32 v3, v4, v3
	v_add_f32_e32 v3, v5, v3
	ds_bpermute_b32 v4, v27, v3
	v_and_b32_e32 v27, -2, v47
	v_mul_u32_u24_e32 v17, 0x110, v17
	v_add3_u32 v54, 0, v27, v17
	s_waitcnt lgkmcnt(0)
	v_add_f32_e32 v3, v3, v4
	v_fmamk_f32 v3, v3, 0x3c800000, v148
	v_cmp_gt_f32_e32 vcc, s98, v3
	v_mul_f32_e32 v4, 0x4b800000, v3
	s_nop 0
	v_cndmask_b32_e32 v3, v3, v4, vcc
	v_rsq_f32_e32 v3, v3
	s_nop 0
	v_mul_f32_e32 v4, 0x45800000, v3
	v_cndmask_b32_e32 v53, v3, v4, vcc
	v_mul_f32_e32 v28, v2, v53
	global_load_dwordx4 v[2:5], v30, s[40:41] offset:48
	global_load_dwordx4 v[6:9], v30, s[40:41] offset:32
	global_load_dwordx4 v[56:59], v30, s[40:41] offset:16
	global_load_dwordx4 v[60:63], v30, s[40:41]
	global_load_dwordx4 v[64:67], v30, s[0:1] offset:48
	global_load_dwordx4 v[68:71], v30, s[0:1] offset:32
	global_load_dwordx4 v[72:75], v30, s[0:1] offset:16
	global_load_dwordx4 v[76:79], v30, s[0:1]
	v_mul_f32_e32 v10, v10, v53
	v_mul_f32_e32 v17, v20, v53
	v_mul_f32_e32 v15, v15, v53
	v_mul_f32_e32 v13, v13, v53
	v_mul_f32_e32 v12, v12, v53
	v_mul_f32_e32 v11, v11, v53
	v_mul_f32_e32 v55, v26, v53
	s_waitcnt vmcnt(1)
	v_fmac_f32_e32 v75, v59, v10
	v_cvt_pk_bf16_f32 v10, v75, s0
	ds_write_b16 v54, v10 offset:1904
	v_mul_f32_e32 v10, v25, v53
	v_fma_f32 v6, v6, v10, v68
	v_cvt_pk_bf16_f32 v6, v6, s0
	ds_write_b16 v54, v6 offset:2176
	v_mul_f32_e32 v6, v24, v53
	v_fma_f32 v6, v7, v6, v69
	v_cvt_pk_bf16_f32 v6, v6, s0
	ds_write_b16 v54, v6 offset:2448
	v_mul_f32_e32 v6, v23, v53
	v_fma_f32 v6, v8, v6, v70
	v_cvt_pk_bf16_f32 v6, v6, s0
	ds_write_b16 v54, v6 offset:2720
	v_mul_f32_e32 v6, v22, v53
	v_fmac_f32_e32 v71, v9, v6
	v_cvt_pk_bf16_f32 v6, v71, s0
	ds_write_b16 v54, v6 offset:2992
	v_mul_f32_e32 v6, v21, v53
	v_fma_f32 v2, v2, v6, v64
	v_cvt_pk_bf16_f32 v2, v2, s0
	ds_write_b16 v54, v2 offset:3264
	v_mul_f32_e32 v2, v19, v53
	v_fma_f32 v2, v3, v2, v65
	v_cvt_pk_bf16_f32 v2, v2, s0
	ds_write_b16 v54, v2 offset:3536
	v_mul_f32_e32 v2, v16, v53
	s_waitcnt vmcnt(0)
	v_fma_f32 v17, v61, v17, v77
	v_fma_f32 v2, v4, v2, v66
	v_cvt_pk_bf16_f32 v17, v17, s0
	v_cvt_pk_bf16_f32 v2, v2, s0
	ds_write_b16 v54, v17 offset:272
	v_mul_f32_e32 v17, v18, v53
	ds_write_b16 v54, v2 offset:3808
	v_mul_f32_e32 v2, v14, v53
	v_fma_f32 v28, v60, v28, v76
	v_fma_f32 v17, v62, v17, v78
	v_fmac_f32_e32 v79, v63, v15
	v_fma_f32 v13, v56, v13, v72
	v_fma_f32 v12, v57, v12, v73
	v_fma_f32 v11, v58, v11, v74
	v_fmac_f32_e32 v67, v5, v2
	v_cvt_pk_bf16_f32 v28, v28, s0
	v_cvt_pk_bf16_f32 v17, v17, s0
	v_cvt_pk_bf16_f32 v15, v79, s0
	v_cvt_pk_bf16_f32 v13, v13, s0
	v_cvt_pk_bf16_f32 v12, v12, s0
	v_cvt_pk_bf16_f32 v11, v11, s0
	v_cvt_pk_bf16_f32 v2, v67, s0
	ds_write_b16 v54, v28
	ds_write_b16 v54, v17 offset:544
	ds_write_b16 v54, v15 offset:816
	ds_write_b16 v54, v13 offset:1088
	ds_write_b16 v54, v12 offset:1360
	ds_write_b16 v54, v11 offset:1632
	ds_write_b16 v54, v2 offset:4080
	global_load_dwordx4 v[2:5], v30, s[40:41] offset:112
	global_load_dwordx4 v[6:9], v30, s[40:41] offset:96
	global_load_dwordx4 v[10:13], v30, s[40:41] offset:80
	global_load_dwordx4 v[26:29], v30, s[40:41] offset:64
	global_load_dwordx4 v[14:17], v30, s[0:1] offset:112
	global_load_dwordx4 v[18:21], v30, s[0:1] offset:96
	global_load_dwordx4 v[22:25], v30, s[0:1] offset:80
	s_nop 0
	global_load_dwordx4 v[30:33], v30, s[0:1] offset:64
	s_waitcnt vmcnt(0)
	v_fma_f32 v26, v26, v55, v30
	v_cvt_pk_bf16_f32 v26, v26, s0
	ds_write_b16 v54, v26 offset:4352
	v_mul_f32_e32 v26, v52, v53
	v_fma_f32 v26, v27, v26, v31
	v_cvt_pk_bf16_f32 v26, v26, s0
	ds_write_b16 v54, v26 offset:4624
	v_mul_f32_e32 v26, v51, v53
	v_fma_f32 v26, v28, v26, v32
	v_cvt_pk_bf16_f32 v26, v26, s0
	ds_write_b16 v54, v26 offset:4896
	v_mul_f32_e32 v26, v50, v53
	v_fmac_f32_e32 v33, v29, v26
	v_cvt_pk_bf16_f32 v26, v33, s0
	ds_write_b16 v54, v26 offset:5168
	v_mul_f32_e32 v26, v49, v53
	v_fma_f32 v10, v10, v26, v22
	v_cvt_pk_bf16_f32 v10, v10, s0
	ds_write_b16 v54, v10 offset:5440
	v_mul_f32_e32 v10, v48, v53
	v_fma_f32 v10, v11, v10, v23
	v_cvt_pk_bf16_f32 v10, v10, s0
	ds_write_b16 v54, v10 offset:5712
	v_mul_f32_e32 v10, v44, v53
	v_fma_f32 v10, v12, v10, v24
	v_cvt_pk_bf16_f32 v10, v10, s0
	ds_write_b16 v54, v10 offset:5984
	v_mul_f32_e32 v10, v45, v53
	v_fmac_f32_e32 v25, v13, v10
	v_cvt_pk_bf16_f32 v10, v25, s0
	ds_write_b16 v54, v10 offset:6256
	v_mul_f32_e32 v10, v42, v53
	v_fma_f32 v6, v6, v10, v18
	v_cvt_pk_bf16_f32 v6, v6, s0
	ds_write_b16 v54, v6 offset:6528
	v_mul_f32_e32 v6, v43, v53
	v_fma_f32 v6, v6, v7, v19
	v_cvt_pk_bf16_f32 v6, v6, s0
	ds_write_b16 v54, v6 offset:6800
	v_mul_f32_e32 v6, v40, v53
	v_fma_f32 v6, v6, v8, v20
	v_cvt_pk_bf16_f32 v6, v6, s0
	ds_write_b16 v54, v6 offset:7072
	v_mul_f32_e32 v6, v41, v53
	v_fmac_f32_e32 v21, v6, v9
	v_cvt_pk_bf16_f32 v6, v21, s0
	ds_write_b16 v54, v6 offset:7344
	v_mul_f32_e32 v6, v38, v53
	v_fma_f32 v2, v6, v2, v14
	v_cvt_pk_bf16_f32 v2, v2, s0
	ds_write_b16 v54, v2 offset:7616
	v_mul_f32_e32 v2, v39, v53
	v_fma_f32 v2, v2, v3, v15
	v_cvt_pk_bf16_f32 v2, v2, s0
	ds_write_b16 v54, v2 offset:7888
	v_mul_f32_e32 v2, v36, v53
	v_fma_f32 v2, v2, v4, v16
	v_cvt_pk_bf16_f32 v2, v2, s0
	ds_write_b16 v54, v2 offset:8160
	v_mul_f32_e32 v2, v37, v53
	v_fmac_f32_e32 v17, v2, v5
	v_cvt_pk_bf16_f32 v2, v17, s0
	v_readlane_b32 s0, v246, 29
	s_or_b32 s0, s13, s0
	s_ashr_i32 s1, s0, 31
	s_lshl_b64 s[40:41], s[0:1], 15
	v_bfe_u32 v44, v47, 4, 2
	s_add_u32 s40, s42, s40
	ds_write_b16 v54, v2 offset:8432
	s_addc_u32 s41, s43, s41
	v_lshlrev_b32_e32 v2, 4, v44
	v_mov_b32_e32 v3, v0
	v_lshl_add_u64 v[32:33], s[40:41], 0, v[2:3]
	v_mul_u32_u24_e32 v3, 0x110, v46
	v_add3_u32 v45, 0, v2, v3
	v_lshlrev_b32_e32 v2, 7, v46
	v_lshl_or_b32 v40, v1, 12, v2
	v_ashrrev_i32_e32 v41, 31, v40
	v_lshl_add_u64 v[2:3], v[40:41], 1, v[32:33]
	v_or_b32_e32 v40, 0x800, v40
	v_ashrrev_i32_e32 v41, 31, v40
	s_waitcnt lgkmcnt(0)
	s_barrier
	v_lshl_add_u64 v[32:33], v[40:41], 1, v[32:33]
	ds_read_b128 v[4:7], v45
	ds_read_b128 v[8:11], v45 offset:4352
	ds_read_b128 v[12:15], v45 offset:8704
	ds_read_b128 v[16:19], v45 offset:13056
	global_load_dwordx4 v[20:23], v[2:3], off
	global_load_dwordx4 v[40:43], v[32:33], off
	global_load_dwordx4 v[72:75], v[2:3], off offset:64
	global_load_dwordx4 v[76:79], v[32:33], off offset:64
	global_load_dwordx4 v[80:83], v[2:3], off offset:128
	global_load_dwordx4 v[84:87], v[32:33], off offset:128
	global_load_dwordx4 v[88:91], v[2:3], off offset:192
	s_waitcnt vmcnt(6) lgkmcnt(3)
	v_mfma_f32_16x16x32_bf16 v[24:27], v[4:7], v[20:23], 0
	v_lshl_or_b32 v1, v1, 5, v46
	s_waitcnt lgkmcnt(2)
	v_mfma_f32_16x16x32_bf16 v[28:31], v[8:11], v[20:23], 0
	s_waitcnt lgkmcnt(1)
	v_mfma_f32_16x16x32_bf16 v[36:39], v[12:15], v[20:23], 0
	s_waitcnt lgkmcnt(0)
	v_mfma_f32_16x16x32_bf16 v[20:23], v[16:19], v[20:23], 0
	s_waitcnt vmcnt(5)
	v_mfma_f32_16x16x32_bf16 v[4:7], v[4:7], v[40:43], 0
	v_mfma_f32_16x16x32_bf16 v[8:11], v[8:11], v[40:43], 0
	v_mfma_f32_16x16x32_bf16 v[12:15], v[12:15], v[40:43], 0
	v_mfma_f32_16x16x32_bf16 v[16:19], v[16:19], v[40:43], 0
	ds_read_b128 v[40:43], v45 offset:64
	ds_read_b128 v[48:51], v45 offset:4416
	ds_read_b128 v[52:55], v45 offset:8768
	ds_read_b128 v[56:59], v45 offset:13120
	s_waitcnt vmcnt(4) lgkmcnt(3)
	v_mfma_f32_16x16x32_bf16 v[24:27], v[40:43], v[72:75], v[24:27]
	s_waitcnt lgkmcnt(2)
	v_mfma_f32_16x16x32_bf16 v[28:31], v[48:51], v[72:75], v[28:31]
	s_waitcnt lgkmcnt(1)
	v_mfma_f32_16x16x32_bf16 v[36:39], v[52:55], v[72:75], v[36:39]
	s_waitcnt lgkmcnt(0)
	v_mfma_f32_16x16x32_bf16 v[20:23], v[56:59], v[72:75], v[20:23]
	s_waitcnt vmcnt(3)
	v_mfma_f32_16x16x32_bf16 v[4:7], v[40:43], v[76:79], v[4:7]
	v_mfma_f32_16x16x32_bf16 v[8:11], v[48:51], v[76:79], v[8:11]
	v_mfma_f32_16x16x32_bf16 v[12:15], v[52:55], v[76:79], v[12:15]
	v_mfma_f32_16x16x32_bf16 v[16:19], v[56:59], v[76:79], v[16:19]
	ds_read_b128 v[40:43], v45 offset:128
	ds_read_b128 v[48:51], v45 offset:4480
	ds_read_b128 v[52:55], v45 offset:8832
	ds_read_b128 v[56:59], v45 offset:13184
	s_waitcnt vmcnt(2) lgkmcnt(3)
	v_mfma_f32_16x16x32_bf16 v[24:27], v[40:43], v[80:83], v[24:27]
	s_waitcnt lgkmcnt(2)
	v_mfma_f32_16x16x32_bf16 v[28:31], v[48:51], v[80:83], v[28:31]
	s_waitcnt lgkmcnt(1)
	v_mfma_f32_16x16x32_bf16 v[36:39], v[52:55], v[80:83], v[36:39]
	s_waitcnt lgkmcnt(0)
	v_mfma_f32_16x16x32_bf16 v[60:63], v[56:59], v[80:83], v[20:23]
	s_nop 2
	s_waitcnt vmcnt(1)
	v_mfma_f32_16x16x32_bf16 v[4:7], v[40:43], v[84:87], v[4:7]
	v_mfma_f32_16x16x32_bf16 v[8:11], v[48:51], v[84:87], v[8:11]
	v_mfma_f32_16x16x32_bf16 v[40:43], v[52:55], v[84:87], v[12:15]
	v_mfma_f32_16x16x32_bf16 v[48:51], v[56:59], v[84:87], v[16:19]
	s_nop 1
	ds_read_b128 v[12:15], v45 offset:192
	ds_read_b128 v[52:55], v45 offset:4544
	ds_read_b128 v[56:59], v45 offset:8896
	ds_read_b128 v[64:67], v45 offset:13248
	s_waitcnt vmcnt(0) lgkmcnt(3)
	v_mfma_f32_16x16x32_bf16 v[68:71], v[12:15], v[88:91], v[24:27]
	s_waitcnt lgkmcnt(2)
	v_mfma_f32_16x16x32_bf16 v[26:29], v[52:55], v[88:91], v[28:31]
	s_nop 2
	global_load_dwordx4 v[30:33], v[32:33], off offset:192
	s_waitcnt lgkmcnt(1)
	v_mfma_f32_16x16x32_bf16 v[22:25], v[56:59], v[88:91], v[36:39]
	s_waitcnt lgkmcnt(0)
	v_mfma_f32_16x16x32_bf16 v[18:21], v[64:67], v[88:91], v[60:63]
	s_waitcnt vmcnt(0)
	v_mfma_f32_16x16x32_bf16 v[14:17], v[12:15], v[30:33], v[4:7]
	v_mfma_f32_16x16x32_bf16 v[10:13], v[52:55], v[30:33], v[8:11]
	v_mfma_f32_16x16x32_bf16 v[6:9], v[56:59], v[30:33], v[40:43]
	v_mfma_f32_16x16x32_bf16 v[2:5], v[64:67], v[30:33], v[48:51]
	v_lshl_add_u32 v30, s0, 7, v1
	v_ashrrev_i32_e32 v31, 31, v30
	v_add_u32_e32 v1, s12, v1
	v_lshl_add_u64 v[32:33], v[30:31], 2, s[74:75]
	v_mad_i64_i32 v[38:39], s[0:1], v1, s9, v[34:35]
	v_lshl_or_b32 v30, v44, 3, s2
	v_mov_b32_e32 v31, v0
	v_lshl_add_u64 v[38:39], v[38:39], 0, v[30:31]
	global_load_dword v36, v[32:33], off
	global_load_dwordx2 v[40:41], v[38:39], off offset:2560
	global_load_dwordx2 v[42:43], v[38:39], off offset:3584
	s_mov_b32 s52, 0x18200
	s_mov_b32 s53, 0
	v_lshl_add_u64 v[72:73], s[52:53], 0, v[38:39]
	global_load_dword v242, v[32:33], off offset:64
	global_load_dwordx2 v[152:153], v[38:39], off offset:2592
	global_load_dwordx2 v[154:155], v[38:39], off offset:3616
	global_load_dwordx2 v[156:157], v[38:39], off offset:2624
	global_load_dwordx2 v[158:159], v[38:39], off offset:3648
	global_load_dwordx2 v[160:161], v[38:39], off offset:2656
	global_load_dwordx2 v[162:163], v[38:39], off offset:3680
	global_load_dwordx2 v[164:165], v[72:73], off offset:2560
	global_load_dwordx2 v[166:167], v[72:73], off offset:3584
	global_load_dwordx2 v[168:169], v[72:73], off offset:2592
	global_load_dwordx2 v[170:171], v[72:73], off offset:3616
	global_load_dwordx2 v[234:235], v[72:73], off offset:2624
	global_load_dwordx2 v[236:237], v[72:73], off offset:3648
	global_load_dwordx2 v[238:239], v[72:73], off offset:2656
	global_load_dwordx2 v[240:241], v[72:73], off offset:3680
	v_or_b32_e32 v1, 16, v1
	v_readlane_b32 s64, v247, 53
	v_readlane_b32 s72, v247, 61
	v_readlane_b32 s65, v247, 54
	v_readlane_b32 s66, v247, 55
	v_readlane_b32 s67, v247, 56
	v_readlane_b32 s68, v247, 57
	v_readlane_b32 s69, v247, 58
	v_readlane_b32 s70, v247, 59
	v_readlane_b32 s71, v247, 60
	v_readlane_b32 s73, v247, 62
	v_readlane_b32 s74, v247, 63
	v_readlane_b32 s75, v246, 0
	v_readlane_b32 s76, v246, 1
	v_readlane_b32 s77, v246, 2
	v_readlane_b32 s78, v246, 3
	v_readlane_b32 s79, v246, 4
	v_readlane_b32 s72, v246, 60
	s_waitcnt vmcnt(0)
	s_cmp_eq_u32 s100, 1
	s_cbranch_scc0 .LmixcSGU_skip
	s_and_saveexec_b64 s[52:53], s[46:47]
	s_cbranch_execz .LmixcSGU_done
	v_mov_b32_e32 v250, s8
	ds_write_b32 v250, v249

.LmixcSGU_skip:
	v_and_b32_e32 v49, 0xffff0000, v40
	v_lshlrev_b32_e32 v44, 16, v42
	v_mul_f32_e32 v37, 0xbfb8aa3b, v44
	v_exp_f32_e32 v37, v37
	v_and_b32_e32 v45, 0xffff0000, v42
	v_lshlrev_b32_e32 v48, 16, v40
	v_add_f32_e32 v37, 1.0, v37
	v_rcp_f32_e32 v46, v37
	v_pk_add_f32 v[50:51], v[68:69], v[36:37] op_sel_hi:[1,0]
	v_mul_f32_e32 v37, 0xbfb8aa3b, v45
	v_exp_f32_e32 v37, v37
	v_pk_mul_f32 v[48:49], v[50:51], v[48:49]
	v_add_f32_e32 v37, 1.0, v37
	v_rcp_f32_e32 v47, v37
	s_nop 0
	v_pk_mul_f32 v[44:45], v[46:47], v[44:45]
	s_nop 0
	v_pk_mul_f32 v[44:45], v[48:49], v[44:45]
	v_and_b32_e32 v47, 0xffff0000, v41
	v_cvt_pk_bf16_f32 v40, v44, v45
	v_lshlrev_b32_e32 v44, 16, v43
	v_mul_f32_e32 v37, 0xbfb8aa3b, v44
	v_exp_f32_e32 v37, v37
	v_and_b32_e32 v45, 0xffff0000, v43
	v_lshlrev_b32_e32 v46, 16, v41
	v_add_f32_e32 v37, 1.0, v37
	v_rcp_f32_e32 v42, v37
	v_pk_add_f32 v[48:49], v[70:71], v[36:37] op_sel_hi:[1,0]
	v_mul_f32_e32 v37, 0xbfb8aa3b, v45
	v_exp_f32_e32 v37, v37
	v_pk_mul_f32 v[46:47], v[48:49], v[46:47]
	v_add_f32_e32 v37, 1.0, v37
	v_rcp_f32_e32 v43, v37
	s_nop 0
	v_pk_mul_f32 v[42:43], v[42:43], v[44:45]
	s_nop 0
	v_pk_mul_f32 v[42:43], v[46:47], v[42:43]
	s_nop 0
	v_cvt_pk_bf16_f32 v41, v42, v43
	global_store_dwordx2 v[38:39], v[40:41], off offset:2560
	v_mov_b32_e32 v40, v152
	v_mov_b32_e32 v41, v153
	s_nop 0
	v_mov_b32_e32 v42, v154
	v_mov_b32_e32 v43, v155
	v_and_b32_e32 v49, 0xffff0000, v40
	v_lshlrev_b32_e32 v44, 16, v42
	v_mul_f32_e32 v37, 0xbfb8aa3b, v44
	v_exp_f32_e32 v37, v37
	v_and_b32_e32 v45, 0xffff0000, v42
	v_lshlrev_b32_e32 v48, 16, v40
	v_lshlrev_b32_e32 v42, 16, v41
	v_add_f32_e32 v37, 1.0, v37
	v_rcp_f32_e32 v46, v37
	v_pk_add_f32 v[26:27], v[26:27], v[36:37] op_sel_hi:[1,0]
	v_mul_f32_e32 v37, 0xbfb8aa3b, v45
	v_exp_f32_e32 v37, v37
	v_pk_mul_f32 v[26:27], v[26:27], v[48:49]
	v_add_f32_e32 v37, 1.0, v37
	v_rcp_f32_e32 v47, v37
	v_pk_add_f32 v[28:29], v[28:29], v[36:37] op_sel_hi:[1,0]
	v_pk_add_f32 v[22:23], v[22:23], v[36:37] op_sel_hi:[1,0]
	v_pk_add_f32 v[24:25], v[24:25], v[36:37] op_sel_hi:[1,0]
	v_pk_mul_f32 v[44:45], v[46:47], v[44:45]
	v_pk_add_f32 v[18:19], v[18:19], v[36:37] op_sel_hi:[1,0]
	v_pk_mul_f32 v[26:27], v[26:27], v[44:45]
	v_lshlrev_b32_e32 v44, 16, v43
	v_cvt_pk_bf16_f32 v26, v26, v27
	v_mul_f32_e32 v27, 0xbfb8aa3b, v44
	v_exp_f32_e32 v27, v27
	v_and_b32_e32 v45, 0xffff0000, v43
	v_and_b32_e32 v43, 0xffff0000, v41
	v_pk_mul_f32 v[28:29], v[28:29], v[42:43]
	v_add_f32_e32 v27, 1.0, v27
	v_rcp_f32_e32 v40, v27
	v_mul_f32_e32 v27, 0xbfb8aa3b, v45
	v_exp_f32_e32 v27, v27
	v_pk_add_f32 v[20:21], v[20:21], v[36:37] op_sel_hi:[1,0]
	v_add_f32_e32 v27, 1.0, v27
	v_rcp_f32_e32 v41, v27
	s_nop 0
	v_pk_mul_f32 v[40:41], v[40:41], v[44:45]
	s_nop 0
	v_pk_mul_f32 v[28:29], v[28:29], v[40:41]
	s_nop 0
	v_cvt_pk_bf16_f32 v27, v28, v29
	global_store_dwordx2 v[38:39], v[26:27], off offset:2592
	v_mov_b32_e32 v26, v156
	v_mov_b32_e32 v27, v157
	s_nop 0
	v_mov_b32_e32 v28, v158
	v_mov_b32_e32 v29, v159
	v_and_b32_e32 v45, 0xffff0000, v26
	v_and_b32_e32 v41, 0xffff0000, v28
	v_lshlrev_b32_e32 v40, 16, v28
	v_mul_f32_e32 v28, 0xbfb8aa3b, v40
	v_lshlrev_b32_e32 v44, 16, v26
	v_mul_f32_e32 v26, 0xbfb8aa3b, v41
	v_exp_f32_e32 v28, v28
	v_exp_f32_e32 v26, v26
	v_pk_mul_f32 v[22:23], v[22:23], v[44:45]
	v_add_f32_e32 v28, 1.0, v28
	v_add_f32_e32 v26, 1.0, v26
	v_rcp_f32_e32 v42, v28
	v_rcp_f32_e32 v43, v26
	v_lshlrev_b32_e32 v28, 16, v27
	v_pk_mul_f32 v[40:41], v[42:43], v[40:41]
	s_nop 0
	v_pk_mul_f32 v[22:23], v[22:23], v[40:41]
	v_lshlrev_b32_e32 v40, 16, v29
	v_cvt_pk_bf16_f32 v22, v22, v23
	v_mul_f32_e32 v23, 0xbfb8aa3b, v40
	v_exp_f32_e32 v23, v23
	v_and_b32_e32 v41, 0xffff0000, v29
	v_and_b32_e32 v29, 0xffff0000, v27
	v_pk_mul_f32 v[24:25], v[24:25], v[28:29]
	v_add_f32_e32 v23, 1.0, v23
	v_rcp_f32_e32 v26, v23
	v_mul_f32_e32 v23, 0xbfb8aa3b, v41
	v_exp_f32_e32 v23, v23
	s_nop 0
	v_add_f32_e32 v23, 1.0, v23
	v_rcp_f32_e32 v27, v23
	s_nop 0
	v_pk_mul_f32 v[26:27], v[26:27], v[40:41]
	s_nop 0
	v_pk_mul_f32 v[24:25], v[24:25], v[26:27]
	s_nop 0
	v_cvt_pk_bf16_f32 v23, v24, v25
	global_store_dwordx2 v[38:39], v[22:23], off offset:2624
	v_mov_b32_e32 v22, v160
	v_mov_b32_e32 v23, v161
	s_nop 0
	v_mov_b32_e32 v24, v162
	v_mov_b32_e32 v25, v163
	v_and_b32_e32 v41, 0xffff0000, v22
	v_and_b32_e32 v27, 0xffff0000, v24
	v_lshlrev_b32_e32 v26, 16, v24
	v_mul_f32_e32 v24, 0xbfb8aa3b, v26
	v_lshlrev_b32_e32 v40, 16, v22
	v_mul_f32_e32 v22, 0xbfb8aa3b, v27
	v_exp_f32_e32 v24, v24
	v_exp_f32_e32 v22, v22
	v_pk_mul_f32 v[18:19], v[18:19], v[40:41]
	v_add_f32_e32 v24, 1.0, v24
	v_add_f32_e32 v22, 1.0, v22
	v_rcp_f32_e32 v28, v24
	v_rcp_f32_e32 v29, v22
	v_lshlrev_b32_e32 v24, 16, v23
	v_pk_mul_f32 v[26:27], v[28:29], v[26:27]
	s_nop 0
	v_pk_mul_f32 v[18:19], v[18:19], v[26:27]
	v_lshlrev_b32_e32 v26, 16, v25
	v_cvt_pk_bf16_f32 v18, v18, v19
	v_mul_f32_e32 v19, 0xbfb8aa3b, v26
	v_exp_f32_e32 v19, v19
	v_and_b32_e32 v27, 0xffff0000, v25
	v_and_b32_e32 v25, 0xffff0000, v23
	v_pk_mul_f32 v[20:21], v[20:21], v[24:25]
	v_add_f32_e32 v19, 1.0, v19
	v_rcp_f32_e32 v22, v19
	v_mul_f32_e32 v19, 0xbfb8aa3b, v27
	v_exp_f32_e32 v19, v19
	s_nop 0
	v_add_f32_e32 v19, 1.0, v19
	v_rcp_f32_e32 v23, v19
	s_nop 0
	v_pk_mul_f32 v[22:23], v[22:23], v[26:27]
	s_nop 0
	v_pk_mul_f32 v[20:21], v[20:21], v[22:23]
	s_nop 0
	v_cvt_pk_bf16_f32 v19, v20, v21
	v_mad_i64_i32 v[20:21], s[0:1], v1, s9, v[34:35]
	global_store_dwordx2 v[38:39], v[18:19], off offset:2656
	v_lshl_add_u64 v[20:21], v[20:21], 0, v[30:31]
	v_mov_b32_e32 v18, v242
	v_mov_b32_e32 v22, v164
	v_mov_b32_e32 v23, v165
	v_mov_b32_e32 v24, v166
	v_mov_b32_e32 v25, v167
	s_mov_b64 s[0:1], 0
	v_and_b32_e32 v31, 0xffff0000, v22
	v_lshlrev_b32_e32 v26, 16, v24
	v_mul_f32_e32 v1, 0xbfb8aa3b, v26
	v_exp_f32_e32 v1, v1
	v_and_b32_e32 v27, 0xffff0000, v24
	v_lshlrev_b32_e32 v30, 16, v22
	v_pk_add_f32 v[14:15], v[14:15], v[18:19] op_sel_hi:[1,0]
	v_add_f32_e32 v1, 1.0, v1
	v_rcp_f32_e32 v28, v1
	v_mul_f32_e32 v1, 0xbfb8aa3b, v27
	v_exp_f32_e32 v1, v1
	v_pk_mul_f32 v[14:15], v[14:15], v[30:31]
	v_lshlrev_b32_e32 v24, 16, v23
	v_pk_add_f32 v[16:17], v[16:17], v[18:19] op_sel_hi:[1,0]
	v_add_f32_e32 v1, 1.0, v1
	v_rcp_f32_e32 v29, v1
	v_pk_add_f32 v[10:11], v[10:11], v[18:19] op_sel_hi:[1,0]
	v_pk_add_f32 v[12:13], v[12:13], v[18:19] op_sel_hi:[1,0]
	v_pk_add_f32 v[6:7], v[6:7], v[18:19] op_sel_hi:[1,0]
	v_pk_mul_f32 v[26:27], v[28:29], v[26:27]
	v_pk_add_f32 v[8:9], v[8:9], v[18:19] op_sel_hi:[1,0]
	v_pk_mul_f32 v[14:15], v[14:15], v[26:27]
	v_lshlrev_b32_e32 v26, 16, v25
	v_mul_f32_e32 v1, 0xbfb8aa3b, v26
	v_exp_f32_e32 v1, v1
	v_and_b32_e32 v27, 0xffff0000, v25
	v_and_b32_e32 v25, 0xffff0000, v23
	v_pk_mul_f32 v[16:17], v[16:17], v[24:25]
	v_add_f32_e32 v1, 1.0, v1
	v_rcp_f32_e32 v22, v1
	v_mul_f32_e32 v1, 0xbfb8aa3b, v27
	v_exp_f32_e32 v1, v1
	v_cvt_pk_bf16_f32 v14, v14, v15
	v_pk_add_f32 v[2:3], v[2:3], v[18:19] op_sel_hi:[1,0]
	v_pk_add_f32 v[4:5], v[4:5], v[18:19] op_sel_hi:[1,0]
	v_add_f32_e32 v1, 1.0, v1
	v_rcp_f32_e32 v23, v1
	s_nop 0
	v_pk_mul_f32 v[22:23], v[22:23], v[26:27]
	s_nop 0
	v_pk_mul_f32 v[16:17], v[16:17], v[22:23]
	s_nop 0
	v_cvt_pk_bf16_f32 v15, v16, v17
	global_store_dwordx2 v[20:21], v[14:15], off offset:2560
	v_mov_b32_e32 v14, v168
	v_mov_b32_e32 v15, v169
	s_nop 0
	v_mov_b32_e32 v16, v170
	v_mov_b32_e32 v17, v171
	v_and_b32_e32 v27, 0xffff0000, v14
	v_lshlrev_b32_e32 v22, 16, v16
	v_mul_f32_e32 v1, 0xbfb8aa3b, v22
	v_exp_f32_e32 v1, v1
	v_and_b32_e32 v23, 0xffff0000, v16
	v_lshlrev_b32_e32 v26, 16, v14
	v_pk_mul_f32 v[10:11], v[10:11], v[26:27]
	v_add_f32_e32 v1, 1.0, v1
	v_rcp_f32_e32 v24, v1
	v_mul_f32_e32 v1, 0xbfb8aa3b, v23
	v_exp_f32_e32 v1, v1
	v_lshlrev_b32_e32 v16, 16, v15
	v_add_f32_e32 v1, 1.0, v1
	v_rcp_f32_e32 v25, v1
	s_nop 0
	v_pk_mul_f32 v[22:23], v[24:25], v[22:23]
	s_nop 0
	v_pk_mul_f32 v[10:11], v[10:11], v[22:23]
	v_lshlrev_b32_e32 v22, 16, v17
	v_mul_f32_e32 v1, 0xbfb8aa3b, v22
	v_exp_f32_e32 v1, v1
	v_and_b32_e32 v23, 0xffff0000, v17
	v_and_b32_e32 v17, 0xffff0000, v15
	v_pk_mul_f32 v[12:13], v[12:13], v[16:17]
	v_add_f32_e32 v1, 1.0, v1
	v_rcp_f32_e32 v14, v1
	v_mul_f32_e32 v1, 0xbfb8aa3b, v23
	v_exp_f32_e32 v1, v1
	v_cvt_pk_bf16_f32 v10, v10, v11
	v_add_f32_e32 v1, 1.0, v1
	v_rcp_f32_e32 v15, v1
	s_nop 0
	v_pk_mul_f32 v[14:15], v[14:15], v[22:23]
	s_nop 0
	v_pk_mul_f32 v[12:13], v[12:13], v[14:15]
	s_nop 0
	v_cvt_pk_bf16_f32 v11, v12, v13
	global_store_dwordx2 v[20:21], v[10:11], off offset:2592
	v_mov_b32_e32 v10, v234
	v_mov_b32_e32 v11, v235
	s_nop 0
	v_mov_b32_e32 v12, v236
	v_mov_b32_e32 v13, v237
	v_and_b32_e32 v23, 0xffff0000, v10
	v_lshlrev_b32_e32 v14, 16, v12
	v_mul_f32_e32 v1, 0xbfb8aa3b, v14
	v_exp_f32_e32 v1, v1
	v_and_b32_e32 v15, 0xffff0000, v12
	v_lshlrev_b32_e32 v22, 16, v10
	v_pk_mul_f32 v[6:7], v[6:7], v[22:23]
	v_add_f32_e32 v1, 1.0, v1
	v_rcp_f32_e32 v16, v1
	v_mul_f32_e32 v1, 0xbfb8aa3b, v15
	v_exp_f32_e32 v1, v1
	v_lshlrev_b32_e32 v12, 16, v11
	v_add_f32_e32 v1, 1.0, v1
	v_rcp_f32_e32 v17, v1
	s_nop 0
	v_pk_mul_f32 v[14:15], v[16:17], v[14:15]
	s_nop 0
	v_pk_mul_f32 v[6:7], v[6:7], v[14:15]
	v_lshlrev_b32_e32 v14, 16, v13
	v_mul_f32_e32 v1, 0xbfb8aa3b, v14
	v_exp_f32_e32 v1, v1
	v_and_b32_e32 v15, 0xffff0000, v13
	v_and_b32_e32 v13, 0xffff0000, v11
	v_pk_mul_f32 v[8:9], v[8:9], v[12:13]
	v_add_f32_e32 v1, 1.0, v1
	v_rcp_f32_e32 v10, v1
	v_mul_f32_e32 v1, 0xbfb8aa3b, v15
	v_exp_f32_e32 v1, v1
	v_cvt_pk_bf16_f32 v6, v6, v7
	v_add_f32_e32 v1, 1.0, v1
	v_rcp_f32_e32 v11, v1
	s_nop 0
	v_pk_mul_f32 v[10:11], v[10:11], v[14:15]
	s_nop 0
	v_pk_mul_f32 v[8:9], v[8:9], v[10:11]
	s_nop 0
	v_cvt_pk_bf16_f32 v7, v8, v9
	global_store_dwordx2 v[20:21], v[6:7], off offset:2624
	v_mov_b32_e32 v6, v238
	v_mov_b32_e32 v7, v239
	s_nop 0
	v_mov_b32_e32 v8, v240
	v_mov_b32_e32 v9, v241
	v_and_b32_e32 v15, 0xffff0000, v6
	v_lshlrev_b32_e32 v10, 16, v8
	v_mul_f32_e32 v1, 0xbfb8aa3b, v10
	v_exp_f32_e32 v1, v1
	v_and_b32_e32 v11, 0xffff0000, v8
	v_lshlrev_b32_e32 v14, 16, v6
	v_pk_mul_f32 v[2:3], v[2:3], v[14:15]
	v_add_f32_e32 v1, 1.0, v1
	v_rcp_f32_e32 v12, v1
	v_mul_f32_e32 v1, 0xbfb8aa3b, v11
	v_exp_f32_e32 v1, v1
	v_lshlrev_b32_e32 v8, 16, v7
	v_add_f32_e32 v1, 1.0, v1
	v_rcp_f32_e32 v13, v1
	s_nop 0
	v_pk_mul_f32 v[10:11], v[12:13], v[10:11]
	s_nop 0
	v_pk_mul_f32 v[2:3], v[2:3], v[10:11]
	v_lshlrev_b32_e32 v10, 16, v9
	v_mul_f32_e32 v1, 0xbfb8aa3b, v10
	v_exp_f32_e32 v1, v1
	v_and_b32_e32 v11, 0xffff0000, v9
	v_and_b32_e32 v9, 0xffff0000, v7
	v_pk_mul_f32 v[4:5], v[4:5], v[8:9]
	v_add_f32_e32 v1, 1.0, v1
	v_rcp_f32_e32 v6, v1
	v_mul_f32_e32 v1, 0xbfb8aa3b, v11
	v_exp_f32_e32 v1, v1
	v_cvt_pk_bf16_f32 v2, v2, v3
	v_add_f32_e32 v1, 1.0, v1
	v_rcp_f32_e32 v7, v1
	s_nop 0
	v_pk_mul_f32 v[6:7], v[6:7], v[10:11]
	s_nop 0
	v_pk_mul_f32 v[4:5], v[4:5], v[6:7]
	s_nop 0
	v_cvt_pk_bf16_f32 v3, v4, v5
	global_store_dwordx2 v[20:21], v[2:3], off offset:2656

.LBB0_107:
	v_mov_b32_e32 v2, v1
	v_mov_b32_e32 v3, v1
	s_nop 1
	v_permlane32_swap_b32_e32 v2, v3
	v_readlane_b32 s64, v247, 53
	v_readlane_b32 s72, v247, 61
	v_readlane_b32 s65, v247, 54
	v_readlane_b32 s66, v247, 55
	s_waitcnt lgkmcnt(0)
	v_add_f32_e32 v1, v2, v3
	v_div_scale_f32 v2, s[0:1], v1, v1, 1.0
	v_rcp_f32_e32 v3, v2
	v_readlane_b32 s67, v247, 56
	v_readlane_b32 s68, v247, 57
	v_readlane_b32 s69, v247, 58
	v_fma_f32 v4, -v2, v3, 1.0
	v_fmac_f32_e32 v3, v4, v3
	v_div_scale_f32 v4, vcc, 1.0, v1, 1.0
	v_mul_f32_e32 v5, v4, v3
	v_fma_f32 v6, -v2, v5, v4
	v_fmac_f32_e32 v5, v6, v3
	v_fma_f32 v2, -v2, v5, v4
	v_div_fmas_f32 v2, v2, v3, v5
	v_lshlrev_b32_e32 v4, 1, v120
	v_mov_b32_e32 v5, v0
	v_lshl_add_u64 v[4:5], v[112:113], 0, v[4:5]
	global_load_dwordx2 v[6:7], v[4:5], off offset:1536
	global_load_dwordx2 v[154:155], v[4:5], off offset:1552
	global_load_dwordx2 v[156:157], v[4:5], off offset:1568
	global_load_dwordx2 v[158:159], v[4:5], off offset:1584
	global_load_dwordx2 v[160:161], v[4:5], off offset:1600
	global_load_dwordx2 v[162:163], v[4:5], off offset:1616
	global_load_dwordx2 v[164:165], v[4:5], off offset:1632
	global_load_dwordx2 v[166:167], v[4:5], off offset:1648
	v_div_fixup_f32 v2, v2, v1, 1.0
	v_pk_mul_f32 v[12:13], v[32:33], v[2:3] op_sel_hi:[1,0]
	v_readlane_b32 s70, v247, 59
	v_readlane_b32 s71, v247, 60
	v_readlane_b32 s74, v247, 63
	v_readlane_b32 s75, v246, 0
	v_readlane_b32 s76, v246, 1
	v_readlane_b32 s77, v246, 2
	v_readlane_b32 s78, v246, 3
	v_readlane_b32 s79, v246, 4
	v_readlane_b32 s72, v246, 60
	v_readlane_b32 s73, v247, 62
	s_waitcnt vmcnt(0)
	s_cmp_eq_u32 s100, 1
	s_cbranch_scc0 .LmixcA1_skip
	s_and_saveexec_b64 s[52:53], s[46:47]
	s_cbranch_execz .LmixcA1_done
	v_mov_b32_e32 v250, s8
	ds_write_b32 v250, v249

.LmixcA1_skip:
	v_lshlrev_b32_e32 v8, 16, v6
	v_mul_f32_e32 v1, 0xbfb8aa3b, v8
	v_exp_f32_e32 v1, v1
	v_and_b32_e32 v9, 0xffff0000, v6
	v_add_f32_e32 v1, 1.0, v1
	v_rcp_f32_e32 v10, v1
	v_mul_f32_e32 v1, 0xbfb8aa3b, v9
	v_exp_f32_e32 v1, v1
	s_nop 0
	v_add_f32_e32 v1, 1.0, v1
	v_rcp_f32_e32 v11, v1
	s_nop 0
	v_pk_mul_f32 v[8:9], v[10:11], v[8:9]
	s_nop 0
	v_pk_mul_f32 v[8:9], v[12:13], v[8:9]
	v_pk_mul_f32 v[12:13], v[34:35], v[2:3] op_sel_hi:[1,0]
	v_cvt_pk_bf16_f32 v6, v8, v9
	v_lshlrev_b32_e32 v8, 16, v7
	v_mul_f32_e32 v1, 0xbfb8aa3b, v8
	v_exp_f32_e32 v1, v1
	v_and_b32_e32 v9, 0xffff0000, v7
	v_add_f32_e32 v1, 1.0, v1
	v_rcp_f32_e32 v10, v1
	v_mul_f32_e32 v1, 0xbfb8aa3b, v9
	v_exp_f32_e32 v1, v1
	s_nop 0
	v_add_f32_e32 v1, 1.0, v1
	v_rcp_f32_e32 v11, v1
	s_nop 0
	v_pk_mul_f32 v[8:9], v[10:11], v[8:9]
	s_nop 0
	v_pk_mul_f32 v[8:9], v[12:13], v[8:9]
	v_pk_mul_f32 v[12:13], v[36:37], v[2:3] op_sel_hi:[1,0]
	v_cvt_pk_bf16_f32 v7, v8, v9
	global_store_dwordx2 v[4:5], v[6:7], off
	v_mov_b32_e32 v6, v154
	v_mov_b32_e32 v7, v155
	v_lshlrev_b32_e32 v8, 16, v6
	v_mul_f32_e32 v1, 0xbfb8aa3b, v8
	v_exp_f32_e32 v1, v1
	v_and_b32_e32 v9, 0xffff0000, v6
	v_add_f32_e32 v1, 1.0, v1
	v_rcp_f32_e32 v10, v1
	v_mul_f32_e32 v1, 0xbfb8aa3b, v9
	v_exp_f32_e32 v1, v1
	s_nop 0
	v_add_f32_e32 v1, 1.0, v1
	v_rcp_f32_e32 v11, v1
	s_nop 0
	v_pk_mul_f32 v[8:9], v[10:11], v[8:9]
	s_nop 0
	v_pk_mul_f32 v[8:9], v[12:13], v[8:9]
	v_pk_mul_f32 v[12:13], v[38:39], v[2:3] op_sel_hi:[1,0]
	v_cvt_pk_bf16_f32 v6, v8, v9
	v_lshlrev_b32_e32 v8, 16, v7
	v_mul_f32_e32 v1, 0xbfb8aa3b, v8
	v_exp_f32_e32 v1, v1
	v_and_b32_e32 v9, 0xffff0000, v7
	v_add_f32_e32 v1, 1.0, v1
	v_rcp_f32_e32 v10, v1
	v_mul_f32_e32 v1, 0xbfb8aa3b, v9
	v_exp_f32_e32 v1, v1
	s_nop 0
	v_add_f32_e32 v1, 1.0, v1
	v_rcp_f32_e32 v11, v1
	s_nop 0
	v_pk_mul_f32 v[8:9], v[10:11], v[8:9]
	s_nop 0
	v_pk_mul_f32 v[8:9], v[12:13], v[8:9]
	v_pk_mul_f32 v[12:13], v[40:41], v[2:3] op_sel_hi:[1,0]
	v_cvt_pk_bf16_f32 v7, v8, v9
	global_store_dwordx2 v[4:5], v[6:7], off offset:16
	v_mov_b32_e32 v6, v156
	v_mov_b32_e32 v7, v157
	v_lshlrev_b32_e32 v8, 16, v6
	v_mul_f32_e32 v1, 0xbfb8aa3b, v8
	v_exp_f32_e32 v1, v1
	v_and_b32_e32 v9, 0xffff0000, v6
	v_add_f32_e32 v1, 1.0, v1
	v_rcp_f32_e32 v10, v1
	v_mul_f32_e32 v1, 0xbfb8aa3b, v9
	v_exp_f32_e32 v1, v1
	s_nop 0
	v_add_f32_e32 v1, 1.0, v1
	v_rcp_f32_e32 v11, v1
	s_nop 0
	v_pk_mul_f32 v[8:9], v[10:11], v[8:9]
	s_nop 0
	v_pk_mul_f32 v[8:9], v[12:13], v[8:9]
	v_pk_mul_f32 v[12:13], v[42:43], v[2:3] op_sel_hi:[1,0]
	v_cvt_pk_bf16_f32 v6, v8, v9
	v_lshlrev_b32_e32 v8, 16, v7
	v_mul_f32_e32 v1, 0xbfb8aa3b, v8
	v_exp_f32_e32 v1, v1
	v_and_b32_e32 v9, 0xffff0000, v7
	v_add_f32_e32 v1, 1.0, v1
	v_rcp_f32_e32 v10, v1
	v_mul_f32_e32 v1, 0xbfb8aa3b, v9
	v_exp_f32_e32 v1, v1
	s_nop 0
	v_add_f32_e32 v1, 1.0, v1
	v_rcp_f32_e32 v11, v1
	s_nop 0
	v_pk_mul_f32 v[8:9], v[10:11], v[8:9]
	s_nop 0
	v_pk_mul_f32 v[8:9], v[12:13], v[8:9]
	v_pk_mul_f32 v[12:13], v[44:45], v[2:3] op_sel_hi:[1,0]
	v_cvt_pk_bf16_f32 v7, v8, v9
	global_store_dwordx2 v[4:5], v[6:7], off offset:32
	v_mov_b32_e32 v6, v158
	v_mov_b32_e32 v7, v159
	v_lshlrev_b32_e32 v8, 16, v6
	v_mul_f32_e32 v1, 0xbfb8aa3b, v8
	v_exp_f32_e32 v1, v1
	v_and_b32_e32 v9, 0xffff0000, v6
	v_add_f32_e32 v1, 1.0, v1
	v_rcp_f32_e32 v10, v1
	v_mul_f32_e32 v1, 0xbfb8aa3b, v9
	v_exp_f32_e32 v1, v1
	s_nop 0
	v_add_f32_e32 v1, 1.0, v1
	v_rcp_f32_e32 v11, v1
	s_nop 0
	v_pk_mul_f32 v[8:9], v[10:11], v[8:9]
	s_nop 0
	v_pk_mul_f32 v[8:9], v[12:13], v[8:9]
	v_pk_mul_f32 v[12:13], v[46:47], v[2:3] op_sel_hi:[1,0]
	v_cvt_pk_bf16_f32 v6, v8, v9
	v_lshlrev_b32_e32 v8, 16, v7
	v_mul_f32_e32 v1, 0xbfb8aa3b, v8
	v_exp_f32_e32 v1, v1
	v_and_b32_e32 v9, 0xffff0000, v7
	v_add_f32_e32 v1, 1.0, v1
	v_rcp_f32_e32 v10, v1
	v_mul_f32_e32 v1, 0xbfb8aa3b, v9
	v_exp_f32_e32 v1, v1
	s_nop 0
	v_add_f32_e32 v1, 1.0, v1
	v_rcp_f32_e32 v11, v1
	s_nop 0
	v_pk_mul_f32 v[8:9], v[10:11], v[8:9]
	s_nop 0
	v_pk_mul_f32 v[8:9], v[12:13], v[8:9]
	v_pk_mul_f32 v[12:13], v[16:17], v[2:3] op_sel_hi:[1,0]
	v_cvt_pk_bf16_f32 v7, v8, v9
	global_store_dwordx2 v[4:5], v[6:7], off offset:48
	v_mov_b32_e32 v6, v160
	v_mov_b32_e32 v7, v161
	v_lshlrev_b32_e32 v8, 16, v6
	v_mul_f32_e32 v1, 0xbfb8aa3b, v8
	v_exp_f32_e32 v1, v1
	v_and_b32_e32 v9, 0xffff0000, v6
	v_add_f32_e32 v1, 1.0, v1
	v_rcp_f32_e32 v10, v1
	v_mul_f32_e32 v1, 0xbfb8aa3b, v9
	v_exp_f32_e32 v1, v1
	s_nop 0
	v_add_f32_e32 v1, 1.0, v1
	v_rcp_f32_e32 v11, v1
	s_nop 0
	v_pk_mul_f32 v[8:9], v[10:11], v[8:9]
	s_nop 0
	v_pk_mul_f32 v[8:9], v[12:13], v[8:9]
	v_pk_mul_f32 v[12:13], v[18:19], v[2:3] op_sel_hi:[1,0]
	v_cvt_pk_bf16_f32 v6, v8, v9
	v_lshlrev_b32_e32 v8, 16, v7
	v_mul_f32_e32 v1, 0xbfb8aa3b, v8
	v_exp_f32_e32 v1, v1
	v_and_b32_e32 v9, 0xffff0000, v7
	v_add_f32_e32 v1, 1.0, v1
	v_rcp_f32_e32 v10, v1
	v_mul_f32_e32 v1, 0xbfb8aa3b, v9
	v_exp_f32_e32 v1, v1
	s_nop 0
	v_add_f32_e32 v1, 1.0, v1
	v_rcp_f32_e32 v11, v1
	s_nop 0
	v_pk_mul_f32 v[8:9], v[10:11], v[8:9]
	s_nop 0
	v_pk_mul_f32 v[8:9], v[12:13], v[8:9]
	v_pk_mul_f32 v[12:13], v[20:21], v[2:3] op_sel_hi:[1,0]
	v_cvt_pk_bf16_f32 v7, v8, v9
	global_store_dwordx2 v[4:5], v[6:7], off offset:64
	v_mov_b32_e32 v6, v162
	v_mov_b32_e32 v7, v163
	v_lshlrev_b32_e32 v8, 16, v6
	v_mul_f32_e32 v1, 0xbfb8aa3b, v8
	v_exp_f32_e32 v1, v1
	v_and_b32_e32 v9, 0xffff0000, v6
	v_add_f32_e32 v1, 1.0, v1
	v_rcp_f32_e32 v10, v1
	v_mul_f32_e32 v1, 0xbfb8aa3b, v9
	v_exp_f32_e32 v1, v1
	s_nop 0
	v_add_f32_e32 v1, 1.0, v1
	v_rcp_f32_e32 v11, v1
	s_nop 0
	v_pk_mul_f32 v[8:9], v[10:11], v[8:9]
	s_nop 0
	v_pk_mul_f32 v[8:9], v[12:13], v[8:9]
	v_pk_mul_f32 v[12:13], v[22:23], v[2:3] op_sel_hi:[1,0]
	v_cvt_pk_bf16_f32 v6, v8, v9
	v_lshlrev_b32_e32 v8, 16, v7
	v_mul_f32_e32 v1, 0xbfb8aa3b, v8
	v_exp_f32_e32 v1, v1
	v_and_b32_e32 v9, 0xffff0000, v7
	v_add_f32_e32 v1, 1.0, v1
	v_rcp_f32_e32 v10, v1
	v_mul_f32_e32 v1, 0xbfb8aa3b, v9
	v_exp_f32_e32 v1, v1
	s_nop 0
	v_add_f32_e32 v1, 1.0, v1
	v_rcp_f32_e32 v11, v1
	s_nop 0
	v_pk_mul_f32 v[8:9], v[10:11], v[8:9]
	s_nop 0
	v_pk_mul_f32 v[8:9], v[12:13], v[8:9]
	v_pk_mul_f32 v[12:13], v[24:25], v[2:3] op_sel_hi:[1,0]
	v_cvt_pk_bf16_f32 v7, v8, v9
	global_store_dwordx2 v[4:5], v[6:7], off offset:80
	v_mov_b32_e32 v6, v164
	v_mov_b32_e32 v7, v165
	v_lshlrev_b32_e32 v8, 16, v6
	v_mul_f32_e32 v1, 0xbfb8aa3b, v8
	v_exp_f32_e32 v1, v1
	v_and_b32_e32 v9, 0xffff0000, v6
	v_add_f32_e32 v1, 1.0, v1
	v_rcp_f32_e32 v10, v1
	v_mul_f32_e32 v1, 0xbfb8aa3b, v9
	v_exp_f32_e32 v1, v1
	s_nop 0
	v_add_f32_e32 v1, 1.0, v1
	v_rcp_f32_e32 v11, v1
	s_nop 0
	v_pk_mul_f32 v[8:9], v[10:11], v[8:9]
	s_nop 0
	v_pk_mul_f32 v[8:9], v[12:13], v[8:9]
	v_pk_mul_f32 v[12:13], v[26:27], v[2:3] op_sel_hi:[1,0]
	v_cvt_pk_bf16_f32 v6, v8, v9
	v_lshlrev_b32_e32 v8, 16, v7
	v_mul_f32_e32 v1, 0xbfb8aa3b, v8
	v_exp_f32_e32 v1, v1
	v_and_b32_e32 v9, 0xffff0000, v7
	v_add_f32_e32 v1, 1.0, v1
	v_rcp_f32_e32 v10, v1
	v_mul_f32_e32 v1, 0xbfb8aa3b, v9
	v_exp_f32_e32 v1, v1
	s_nop 0
	v_add_f32_e32 v1, 1.0, v1
	v_rcp_f32_e32 v11, v1
	s_nop 0
	v_pk_mul_f32 v[8:9], v[10:11], v[8:9]
	s_nop 0
	v_pk_mul_f32 v[8:9], v[12:13], v[8:9]
	v_pk_mul_f32 v[12:13], v[28:29], v[2:3] op_sel_hi:[1,0]
	v_cvt_pk_bf16_f32 v7, v8, v9
	global_store_dwordx2 v[4:5], v[6:7], off offset:96
	v_mov_b32_e32 v6, v166
	v_mov_b32_e32 v7, v167
	v_pk_mul_f32 v[2:3], v[30:31], v[2:3] op_sel_hi:[1,0]
	v_lshlrev_b32_e32 v8, 16, v6
	v_mul_f32_e32 v1, 0xbfb8aa3b, v8
	v_exp_f32_e32 v1, v1
	v_and_b32_e32 v9, 0xffff0000, v6
	v_add_f32_e32 v1, 1.0, v1
	v_rcp_f32_e32 v10, v1
	v_mul_f32_e32 v1, 0xbfb8aa3b, v9
	v_exp_f32_e32 v1, v1
	s_nop 0
	v_add_f32_e32 v1, 1.0, v1
	v_rcp_f32_e32 v11, v1
	s_nop 0
	v_pk_mul_f32 v[8:9], v[10:11], v[8:9]
	s_nop 0
	v_pk_mul_f32 v[8:9], v[12:13], v[8:9]
	s_nop 0
	v_cvt_pk_bf16_f32 v6, v8, v9
	v_lshlrev_b32_e32 v8, 16, v7
	v_mul_f32_e32 v1, 0xbfb8aa3b, v8
	v_exp_f32_e32 v1, v1
	v_and_b32_e32 v9, 0xffff0000, v7
	v_add_f32_e32 v1, 1.0, v1
	v_rcp_f32_e32 v10, v1
	v_mul_f32_e32 v1, 0xbfb8aa3b, v9
	v_exp_f32_e32 v1, v1
	s_nop 0
	v_add_f32_e32 v1, 1.0, v1
	v_rcp_f32_e32 v11, v1
	s_nop 0
	v_pk_mul_f32 v[8:9], v[10:11], v[8:9]
	s_nop 0
	v_pk_mul_f32 v[2:3], v[2:3], v[8:9]
	s_nop 0
	v_cvt_pk_bf16_f32 v7, v2, v3
	global_store_dwordx2 v[4:5], v[6:7], off offset:112

.LBB0_109:
	s_andn2_b64 vcc, exec, s[0:1]
	s_cbranch_vccnz .LBB0_144
	v_readlane_b32 s0, v245, 1
	v_mov_b32_e32 v1, v149
	s_add_i32 s40, s0, s97
	s_lshr_b32 s12, s40, 8
	v_ashrrev_i32_e32 v2, 1, v1
	s_bfe_u32 s13, s40, 0x50003
	v_and_b32_e32 v12, 0xffffffe0, v2
	v_and_b32_e32 v10, 31, v1
	s_lshl_b32 s0, s12, 12
	v_lshl_add_u32 v13, s13, 7, v12
	s_add_i32 s41, s0, 0x2000
	v_or_b32_e32 v2, v13, v10
	s_and_b32 s42, s97, 7
	v_add_u32_e32 v4, s41, v2
	v_mov_b64_e32 v[2:3], s[34:35]
	v_bfe_u32 v11, v1, 5, 1
	v_mad_i64_i32 v[4:5], s[0:1], v4, s9, v[2:3]
	s_lshl_b32 s2, s42, 7
	v_lshl_add_u64 v[152:153], v[4:5], 0, s[2:3]
	v_lshlrev_b32_e32 v4, 4, v11
	v_mov_b32_e32 v5, v0
	v_lshl_add_u64 v[6:7], v[152:153], 0, v[4:5]
	global_load_dwordx4 v[80:83], v[6:7], off
	global_load_dwordx4 v[84:87], v[6:7], off offset:32
	global_load_dwordx4 v[88:91], v[6:7], off offset:64
	global_load_dwordx4 v[92:95], v[6:7], off offset:96
	s_lshl_b32 s2, s13, 1
	v_sub_u32_e64 v5, s2, 2 clamp
	v_readlane_b32 s0, v246, 34
	s_min_u32 s2, s2, 60
	v_readfirstlane_b32 s13, v5
	s_or_b32 s0, s42, s0
	s_sub_i32 s59, s2, s13
	s_ashr_i32 s1, s0, 31
	s_add_i32 s56, s59, 3
	s_add_i32 s59, s59, 8
	s_cmp_lt_i32 s56, 0
	s_cselect_b64 s[50:51], -1, 0
	s_cmp_gt_i32 s56, -5
	v_ashrrev_i32_e32 v14, 2, v1
	s_cselect_b64 s[52:53], -1, 0
	s_not_b32 s2, s56
	v_lshl_add_u32 v6, s2, 6, v14
	s_lshl_b32 s2, s12, 1
	s_add_i32 s12, s2, s4
	v_lshlrev_b32_e32 v5, 6, v5
	s_ashr_i32 s13, s12, 31
	v_ashrrev_i32_e32 v7, 31, v6
	s_lshl_b32 s2, s40, 4
	v_or_b32_e32 v5, s41, v5
	s_lshl_b64 s[12:13], s[12:13], 15
	v_lshlrev_b64 v[6:7], 7, v[6:7]
	s_and_b32 s40, s2, 64
	v_add_u32_e32 v5, v5, v14
	v_and_b32_e32 v8, 63, v1
	v_lshl_add_u64 v[6:7], v[6:7], 0, s[12:13]
	v_mad_i64_i32 v[2:3], s[12:13], v5, s9, v[2:3]
	s_lshl_b32 s2, s40, 1
	v_cmp_gt_u32_e32 vcc, 32, v8
	v_lshlrev_b32_e32 v8, 4, v1
	s_add_u32 s12, s34, s2
	v_readlane_b32 s64, v246, 5
	v_and_b32_e32 v15, 48, v8
	s_addc_u32 s13, s35, 0
	s_lshl_b64 s[0:1], s[0:1], 2
	v_readlane_b32 s70, v246, 11
	v_mov_b32_e32 v8, v15
	v_mov_b32_e32 v9, v0
	v_readlane_b32 s71, v246, 12
	s_add_u32 s54, s70, s0
	v_lshl_add_u64 v[2:3], v[2:3], 0, s[2:3]
	v_lshl_add_u64 v[156:157], s[12:13], 0, v[8:9]
	s_addc_u32 s55, s71, s1
	s_add_i32 s12, s45, s97
	v_lshl_add_u64 v[154:155], v[2:3], 0, v[8:9]
	v_mul_lo_u32 v2, v14, s39
	s_bfe_u32 s0, s12, 0x50003
	v_add3_u32 v234, 0, v2, v8
	v_lshrrev_b32_e32 v254, 1, v15
	v_add3_u32 v254, 0, v2, v254
	v_add_u32_e32 v8, 0, v4
	v_lshlrev_b32_e32 v151, 2, v11
	v_lshrrev_b32_e32 v2, 2, v1
	v_and_b32_e32 v3, 16, v1
	v_lshlrev_b32_e32 v4, 3, v1
	s_lshl_b32 s2, s40, 2
	s_lshl_b32 s40, s0, 1
	v_and_or_b32 v2, v2, 3, v151
	v_lshlrev_b32_e32 v3, 1, v3
	v_and_b32_e32 v4, 24, v4
	s_min_u32 s41, s40, 2
	s_min_u32 s40, s40, 60
	v_add_u32_e32 v235, 0x9f, v13
	v_add_u32_e32 v236, 0xffffff80, v13
	v_add_u32_e32 v237, 0xffffff9f, v13
	v_add_u32_e32 v238, 0x41, v13
	v_add3_u32 v9, 0, v3, v4
	v_mul_u32_u24_e32 v13, 0x90, v2
	v_lshlrev_b64 v[2:3], 2, v[6:7]
	s_lshl_b32 s13, s0, 7
	v_and_b32_e32 v1, 3, v1
	s_add_i32 s40, s40, s41
	v_lshl_add_u64 v[4:5], s[84:85], 0, v[2:3]
	v_lshl_add_u64 v[2:3], s[86:87], 0, v[2:3]
	v_lshlrev_b32_e32 v162, 4, v1
	s_lshr_b32 s43, s12, 8
	v_add_u32_e32 v1, s13, v14
	s_lshl_b32 s40, s40, 6
	v_mov_b32_e32 v6, v15
	v_mov_b32_e32 v7, v0
	v_lshl_add_u64 v[2:3], v[2:3], 0, s[2:3]
	s_lshl_b32 s0, s43, 1
	v_subrev_u32_e32 v1, s40, v1
	v_lshl_add_u64 v[160:161], v[2:3], 0, v[6:7]
	s_add_i32 s0, s4, s0
	v_add_u32_e32 v2, 0xffffff40, v1
	s_ashr_i32 s1, s0, 31
	v_ashrrev_i32_e32 v3, 31, v2
	s_lshl_b64 s[0:1], s[0:1], 17
	v_lshlrev_b64 v[2:3], 9, v[2:3]
	v_lshl_add_u64 v[2:3], s[0:1], 0, v[2:3]
	s_lshl_b32 s0, s12, 6
	s_and_b32 s0, s0, 0x100
	v_or_b32_e32 v2, s0, v2
	s_lshl_b32 s0, s43, 12
	s_or_b32 s0, s13, s0
	s_lshl_b32 s42, s41, 6
	v_add_u32_e32 v1, s0, v14
	v_subrev_u32_e32 v1, s42, v1
	v_add_u32_e32 v239, 0x2040, v1
	v_sub_u32_e32 v1, v151, v10
	v_mul_u32_u24_e32 v11, 0x90, v10
	v_lshl_add_u64 v[4:5], v[4:5], 0, s[2:3]
	v_sub_u32_e32 v1, v1, v12
	v_cndmask_b32_e64 v233, 0, 1.0, vcc
	s_mov_b32 s60, 0
	v_lshl_add_u64 v[158:159], v[4:5], 0, v[6:7]
	s_sub_i32 s2, s13, s42
	v_mov_b32_e32 v163, v0
	v_lshl_add_u64 v[164:165], s[84:85], 0, v[2:3]
	v_lshl_add_u64 v[166:167], s[86:87], 0, v[2:3]
	v_subrev_u32_e32 v240, s42, v1
	v_add_u32_e32 v241, v8, v11
	v_add_u32_e32 v242, v9, v13
	v_readlane_b32 s65, v246, 6
	v_readlane_b32 s66, v246, 7
	v_readlane_b32 s67, v246, 8
	v_readlane_b32 s68, v246, 9
	v_readlane_b32 s69, v246, 10
	v_readlane_b32 s72, v246, 13
	v_readlane_b32 s73, v246, 14
	v_readlane_b32 s74, v246, 15
	v_readlane_b32 s75, v246, 16
	v_readlane_b32 s76, v246, 17
	v_readlane_b32 s77, v246, 18
	v_readlane_b32 s78, v246, 19
	v_readlane_b32 s79, v246, 20
	s_branch .LBB0_113

.LBB0_123:
	s_andn2_b64 vcc, exec, s[12:13]
	s_cbranch_vccnz .LBB0_125
	v_cvt_pk_bf16_f32 v5, v58, v59
	v_cvt_pk_bf16_f32 v4, v56, v57
	v_cvt_pk_bf16_f32 v3, v62, v63
	v_cvt_pk_bf16_f32 v2, v60, v61
	ds_write_b64 v254, v[2:3]
	ds_write_b64 v254, v[4:5] offset:32
	v_cvt_pk_bf16_f32 v5, v74, v75
	v_cvt_pk_bf16_f32 v4, v72, v73
	v_cvt_pk_bf16_f32 v3, v78, v79
	v_cvt_pk_bf16_f32 v2, v76, v77
	ds_write_b64 v254, v[2:3] offset:9216
	ds_write_b64 v254, v[4:5] offset:9248
	v_cvt_pk_bf16_f32 v5, v50, v51
	v_cvt_pk_bf16_f32 v4, v48, v49
	v_cvt_pk_bf16_f32 v3, v54, v55
	v_cvt_pk_bf16_f32 v2, v52, v53
	ds_write_b64 v254, v[2:3] offset:64
	ds_write_b64 v254, v[4:5] offset:96
	v_cvt_pk_bf16_f32 v5, v66, v67
	v_cvt_pk_bf16_f32 v4, v64, v65
	v_cvt_pk_bf16_f32 v3, v70, v71
	v_cvt_pk_bf16_f32 v2, v68, v69
	ds_write_b64 v254, v[2:3] offset:9280
	ds_write_b64 v254, v[4:5] offset:9312

.LBB0_143:
	v_mov_b32_e32 v1, v243
	v_mov_b32_e32 v2, v243
	v_readlane_b32 s64, v247, 53
	v_readlane_b32 s72, v247, 61
	v_permlane32_swap_b32_e32 v1, v2
	v_readlane_b32 s65, v247, 54
	v_readlane_b32 s66, v247, 55
	v_readlane_b32 s67, v247, 56
	v_readlane_b32 s68, v247, 57
	s_waitcnt lgkmcnt(0)
	v_add_f32_e32 v1, v1, v2
	v_div_scale_f32 v2, s[0:1], v1, v1, 1.0
	v_rcp_f32_e32 v3, v2
	v_readlane_b32 s69, v247, 58
	v_readlane_b32 s70, v247, 59
	v_readlane_b32 s71, v247, 60
	v_fma_f32 v4, -v2, v3, 1.0
	v_fmac_f32_e32 v3, v4, v3
	v_div_scale_f32 v4, vcc, 1.0, v1, 1.0
	v_mul_f32_e32 v5, v4, v3
	v_fma_f32 v6, -v2, v5, v4
	v_fmac_f32_e32 v5, v6, v3
	v_fma_f32 v2, -v2, v5, v4
	v_div_fmas_f32 v2, v2, v3, v5
	v_lshlrev_b32_e32 v4, 1, v151
	v_mov_b32_e32 v5, v0
	v_lshl_add_u64 v[4:5], v[152:153], 0, v[4:5]
	global_load_dwordx2 v[6:7], v[4:5], off offset:1536
	global_load_dwordx2 v[154:155], v[4:5], off offset:1552
	global_load_dwordx2 v[156:157], v[4:5], off offset:1568
	global_load_dwordx2 v[158:159], v[4:5], off offset:1584
	global_load_dwordx2 v[160:161], v[4:5], off offset:1600
	global_load_dwordx2 v[162:163], v[4:5], off offset:1616
	global_load_dwordx2 v[164:165], v[4:5], off offset:1632
	global_load_dwordx2 v[166:167], v[4:5], off offset:1648
	v_div_fixup_f32 v2, v2, v1, 1.0
	v_pk_mul_f32 v[12:13], v[32:33], v[2:3] op_sel_hi:[1,0]
	v_readlane_b32 s74, v247, 63
	v_readlane_b32 s75, v246, 0
	v_readlane_b32 s76, v246, 1
	v_readlane_b32 s77, v246, 2
	v_readlane_b32 s78, v246, 3
	v_readlane_b32 s79, v246, 4
	v_readlane_b32 s72, v246, 60
	v_readlane_b32 s73, v247, 62
	s_waitcnt vmcnt(0)
	s_cmp_eq_u32 s100, 1
	s_cbranch_scc0 .LmixcA2_skip
	s_and_saveexec_b64 s[52:53], s[46:47]
	s_cbranch_execz .LmixcA2_done
	v_mov_b32_e32 v250, s8
	ds_write_b32 v250, v249

	.amdhsa_kernel _Z4mega1Piii
		.amdhsa_group_segment_fixed_size 0
		.amdhsa_private_segment_fixed_size 0
		.amdhsa_kernarg_size 464
		.amdhsa_user_sgpr_count 2
		.amdhsa_user_sgpr_dispatch_ptr 0
		.amdhsa_user_sgpr_queue_ptr 0
		.amdhsa_user_sgpr_kernarg_segment_ptr 1
		.amdhsa_user_sgpr_dispatch_id 0
		.amdhsa_user_sgpr_kernarg_preload_length 0
		.amdhsa_user_sgpr_kernarg_preload_offset 0
		.amdhsa_user_sgpr_private_segment_size 0
		.amdhsa_uses_dynamic_stack 0
		.amdhsa_enable_private_segment 0
		.amdhsa_system_sgpr_workgroup_id_x 1
		.amdhsa_system_sgpr_workgroup_id_y 0
		.amdhsa_system_sgpr_workgroup_id_z 0
		.amdhsa_system_sgpr_workgroup_info 0
		.amdhsa_system_vgpr_workitem_id 2
		.amdhsa_next_free_vgpr 256
		.amdhsa_next_free_sgpr 102
		.amdhsa_accum_offset 256
		.amdhsa_reserve_vcc 1
		.amdhsa_float_round_mode_32 0
		.amdhsa_float_round_mode_16_64 0
		.amdhsa_float_denorm_mode_32 3
		.amdhsa_float_denorm_mode_16_64 3
		.amdhsa_dx10_clamp 1
		.amdhsa_ieee_mode 1
		.amdhsa_fp16_overflow 0
		.amdhsa_tg_split 0
		.amdhsa_exception_fp_ieee_invalid_op 0
		.amdhsa_exception_fp_denorm_src 0
		.amdhsa_exception_fp_ieee_div_zero 0
		.amdhsa_exception_fp_ieee_overflow 0
		.amdhsa_exception_fp_ieee_underflow 0
		.amdhsa_exception_fp_ieee_inexact 0
		.amdhsa_exception_int_div_zero 0
	.end_amdhsa_kernel

amdhsa.kernels:
  - .agpr_count:     0
    .args:
      - .offset:         0
        .size:           192
        .value_kind:     by_value
      - .offset:         192
        .size:           4
        .value_kind:     by_value
      - .offset:         196
        .size:           4
        .value_kind:     by_value
      - .offset:         200
        .size:           4
        .value_kind:     by_value
      - .offset:         208
        .size:           4
        .value_kind:     hidden_block_count_x
      - .offset:         212
        .size:           4
        .value_kind:     hidden_block_count_y
      - .offset:         216
        .size:           4
        .value_kind:     hidden_block_count_z
      - .offset:         220
        .size:           2
        .value_kind:     hidden_group_size_x
      - .offset:         222
        .size:           2
        .value_kind:     hidden_group_size_y
      - .offset:         224
        .size:           2
        .value_kind:     hidden_group_size_z
      - .offset:         226
        .size:           2
        .value_kind:     hidden_remainder_x
      - .offset:         228
        .size:           2
        .value_kind:     hidden_remainder_y
      - .offset:         230
        .size:           2
        .value_kind:     hidden_remainder_z
      - .offset:         248
        .size:           8
        .value_kind:     hidden_global_offset_x
      - .offset:         256
        .size:           8
        .value_kind:     hidden_global_offset_y
      - .offset:         264
        .size:           8
        .value_kind:     hidden_global_offset_z
      - .offset:         272
        .size:           2
        .value_kind:     hidden_grid_dims
      - .offset:         296
        .size:           8
        .value_kind:     hidden_multigrid_sync_arg
      - .offset:         328
        .size:           4
        .value_kind:     hidden_dynamic_lds_size
    .group_segment_fixed_size: 0
    .kernarg_segment_align: 8
    .kernarg_segment_size: 464
    .language:       OpenCL C
    .language_version:
      - 2
      - 0
    .max_flat_workgroup_size: 256
    .name:           _Z4mega1Piii
    .private_segment_fixed_size: 0
    .sgpr_count:     108
    .sgpr_spill_count: 200
    .symbol:         _Z4mega1Piii.kd
    .uniform_work_group_size: 1
    .uses_dynamic_stack: false
    .vgpr_count:     256
    .vgpr_spill_count: 0
    .wavefront_size: 64
